# barrier 10 (QKV1 to ATT1) replaced by per-row-block qkv-done counters: an attention workgroup waits only for the row blocks its two units read (ctx block, latent band blocks r-1..r+1)
# speedup vs baseline: 1.0335x; 1.0031x over previous
.LBB0_1035:
	s_waitcnt vmcnt(0)
	s_waitcnt vmcnt(0) lgkmcnt(0)
	s_barrier
	s_mov_b64 s[6:7], exec
	v_readlane_b32 s0, v219, 25
	v_readlane_b32 s1, v219, 26
	s_and_b64 s[0:1], s[6:7], s[0:1]
	s_mov_b64 exec, s[0:1]
	s_cbranch_execz .LBB0_1087
	v_readlane_b32 s0, v219, 27
	v_readlane_b32 s1, v219, 28
	v_readlane_b32 s2, v219, 30
	s_waitcnt vmcnt(0) lgkmcnt(0)
	buffer_inv sc1
	s_and_b32 s3, s2, 31
	s_lshl_b32 s3, s3, 7
	s_add_i32 s3, s3, 0x70
	v_mov_b32_e32 v0, 1
	v_mov_b32_e32 v1, s3
	s_nop 1
	global_atomic_add v1, v0, s[0:1]
	s_lshr_b32 s3, s2, 4
	s_lshl_b32 s3, s3, 7
	s_add_i32 s3, s3, 0x70
	s_mov_b32 s10, 1
.Lqb10_cw:
	v_mov_b32_e32 v1, s3
	s_mov_b32 s15, 0

.Lqb10_cn:
	s_add_i32 s3, s3, 0x80
	s_sub_i32 s10, s10, 1
	s_cmp_lg_u32 s10, 0
	s_cbranch_scc1 .Lqb10_cw
	s_bfe_u32 s11, s2, 0x10002
	s_lshl_b32 s11, s11, 3
	s_add_i32 s11, s11, 16
	s_bfe_u32 s14, s2, 0x30004
	s_sub_i32 s13, s14, 1
	s_max_i32 s13, s13, 0
	s_add_i32 s14, s14, 1
	s_min_i32 s14, s14, 7
	s_sub_i32 s10, s14, s13
	s_add_i32 s10, s10, 1
	s_add_i32 s3, s11, s13
	s_lshl_b32 s3, s3, 7
	s_add_i32 s3, s3, 0x70

.Lqb10_ln:
	s_add_i32 s3, s3, 0x80
	s_sub_i32 s10, s10, 1
	s_cmp_lg_u32 s10, 0
	s_cbranch_scc1 .Lqb10_lw
	s_waitcnt vmcnt(0)
